# GEMM K-loops: setprio raised before the pre-MMA barrier, redundant lgkmcnt(0) and mid-block setprio toggles removed from the MFMA segment
# speedup vs baseline: 1.0103x; 1.0103x over previous
.LBB0_320:
	s_add_u32 s20, s40, 0xfffc0080
	s_addc_u32 s21, s41, -1
	s_add_i32 s77, 0, 0x10000
	s_cmp_eq_u32 s76, 12
	s_cselect_b32 s59, s49, s21
	s_cselect_b32 s58, s55, s20
	s_cselect_b32 s21, s45, s75
	s_cselect_b32 s20, s73, s74
	s_add_i32 s80, 0, 0x14000
	v_add_u32_e32 v60, s77, v183
	v_add_u32_e32 v168, s80, v183
	ds_read_b128 v[48:51], v60
	ds_read_b128 v[52:55], v60 offset:1024
	ds_read_b128 v[56:59], v60 offset:2048
	ds_read_b128 v[60:63], v60 offset:3072
	ds_read_b128 v[164:167], v168
	ds_read_b128 v[170:173], v168 offset:1024
	ds_read_b128 v[174:177], v168 offset:2048
	ds_read_b128 v[178:181], v168 offset:3072
	v_lshl_add_u64 v[228:229], s[40:41], 0, v[162:163]
	s_add_i32 m0, s57, 0xc000
	ds_read_b128 v[204:207], v202
	ds_read_b128 v[208:211], v202 offset:1024
	ds_read_b128 v[212:215], v202 offset:2048
	ds_read_b128 v[216:219], v202 offset:3072
	ds_read_b128 v[220:223], v202 offset:4096
	ds_read_b128 v[224:227], v202 offset:5120
	ds_read_b128 v[240:243], v202 offset:6144
	ds_read_b128 v[244:247], v202 offset:7168
	global_load_lds_dwordx4 v[228:229], off
	v_lshl_add_u64 v[228:229], s[40:41], 0, v[160:161]
	s_add_i32 m0, s57, 0xe000
	s_nop 0
	global_load_lds_dwordx4 v[228:229], off
	s_waitcnt vmcnt(8)
	s_waitcnt lgkmcnt(0)
	s_setprio 1
	s_barrier
	v_mfma_f32_16x16x32_bf16 v[140:143], v[48:51], v[204:207], v[140:143]
	v_mfma_f32_16x16x32_bf16 v[136:139], v[56:59], v[204:207], v[136:139]
	v_mfma_f32_16x16x32_bf16 v[124:127], v[48:51], v[212:215], v[124:127]
	v_mfma_f32_16x16x32_bf16 v[120:123], v[56:59], v[212:215], v[120:123]
	v_mfma_f32_16x16x32_bf16 v[108:111], v[48:51], v[220:223], v[108:111]
	v_mfma_f32_16x16x32_bf16 v[104:107], v[56:59], v[220:223], v[104:107]
	v_mfma_f32_16x16x32_bf16 v[92:95], v[48:51], v[240:243], v[92:95]
	v_mfma_f32_16x16x32_bf16 v[88:91], v[56:59], v[240:243], v[88:91]
	v_mfma_f32_16x16x32_bf16 v[140:143], v[52:55], v[208:211], v[140:143]
	v_mfma_f32_16x16x32_bf16 v[136:139], v[60:63], v[208:211], v[136:139]
	v_mfma_f32_16x16x32_bf16 v[124:127], v[52:55], v[216:219], v[124:127]
	v_mfma_f32_16x16x32_bf16 v[120:123], v[60:63], v[216:219], v[120:123]
	v_mfma_f32_16x16x32_bf16 v[108:111], v[52:55], v[224:227], v[108:111]
	v_mfma_f32_16x16x32_bf16 v[104:107], v[60:63], v[224:227], v[104:107]
	v_mfma_f32_16x16x32_bf16 v[92:95], v[52:55], v[244:247], v[92:95]
	v_mfma_f32_16x16x32_bf16 v[88:91], v[60:63], v[244:247], v[88:91]
	v_mfma_f32_16x16x32_bf16 v[132:135], v[164:167], v[204:207], v[132:135]
	v_mfma_f32_16x16x32_bf16 v[128:131], v[174:177], v[204:207], v[128:131]
	v_mfma_f32_16x16x32_bf16 v[116:119], v[164:167], v[212:215], v[116:119]
	v_mfma_f32_16x16x32_bf16 v[112:115], v[174:177], v[212:215], v[112:115]
	v_mfma_f32_16x16x32_bf16 v[100:103], v[164:167], v[220:223], v[100:103]
	v_mfma_f32_16x16x32_bf16 v[96:99], v[174:177], v[220:223], v[96:99]
	v_mfma_f32_16x16x32_bf16 v[84:87], v[164:167], v[240:243], v[84:87]
	v_mfma_f32_16x16x32_bf16 v[80:83], v[174:177], v[240:243], v[80:83]
	v_mfma_f32_16x16x32_bf16 v[132:135], v[170:173], v[208:211], v[132:135]
	v_mfma_f32_16x16x32_bf16 v[128:131], v[178:181], v[208:211], v[128:131]
	v_mfma_f32_16x16x32_bf16 v[116:119], v[170:173], v[216:219], v[116:119]
	v_mfma_f32_16x16x32_bf16 v[112:115], v[178:181], v[216:219], v[112:115]
	v_mfma_f32_16x16x32_bf16 v[100:103], v[170:173], v[224:227], v[100:103]
	v_mfma_f32_16x16x32_bf16 v[96:99], v[178:181], v[224:227], v[96:99]
	v_mfma_f32_16x16x32_bf16 v[84:87], v[170:173], v[244:247], v[84:87]
	v_mfma_f32_16x16x32_bf16 v[80:83], v[178:181], v[244:247], v[80:83]
	s_barrier
	s_setprio 0
	s_add_i32 s77, s77, s62
	v_lshl_add_u64 v[228:229], s[20:21], 0, v[146:147]
	s_mov_b32 m0, s77
	ds_read_b128 v[204:207], v202 offset:16384
	ds_read_b128 v[208:211], v202 offset:17408
	ds_read_b128 v[212:215], v202 offset:18432
	ds_read_b128 v[216:219], v202 offset:19456
	ds_read_b128 v[220:223], v202 offset:20480
	ds_read_b128 v[224:227], v202 offset:21504
	ds_read_b128 v[240:243], v202 offset:22528
	ds_read_b128 v[244:247], v202 offset:23552
	global_load_lds_dwordx4 v[228:229], off
	s_add_i32 m0, s77, 0x2000
	s_add_u32 s78, s20, 0x40000
	v_lshl_add_u64 v[230:231], s[20:21], 0, v[150:151]
	s_addc_u32 s79, s21, 0
	s_add_i32 s77, s80, s62
	global_load_lds_dwordx4 v[230:231], off
	v_lshl_add_u64 v[232:233], s[78:79], 0, v[146:147]
	s_mov_b32 m0, s77
	v_lshl_add_u64 v[234:235], s[58:59], 0, v[148:149]
	global_load_lds_dwordx4 v[232:233], off
	v_lshl_add_u64 v[232:233], s[78:79], 0, v[150:151]
	s_add_i32 m0, s77, 0x2000
	s_nop 0
	global_load_lds_dwordx4 v[232:233], off
	v_lshl_add_u64 v[232:233], s[58:59], 0, v[144:145]
	s_mov_b32 m0, s57
	s_nop 0
	global_load_lds_dwordx4 v[232:233], off
	s_mov_b32 m0, s65
	s_nop 0
	global_load_lds_dwordx4 v[234:235], off
	s_waitcnt vmcnt(8)
	s_waitcnt lgkmcnt(0)
	s_setprio 1
	s_barrier
	v_mfma_f32_16x16x32_bf16 v[76:79], v[48:51], v[204:207], v[76:79]
	v_mfma_f32_16x16x32_bf16 v[72:75], v[56:59], v[204:207], v[72:75]
	v_mfma_f32_16x16x32_bf16 v[44:47], v[48:51], v[212:215], v[44:47]
	v_mfma_f32_16x16x32_bf16 v[40:43], v[56:59], v[212:215], v[40:43]
	v_mfma_f32_16x16x32_bf16 v[28:31], v[48:51], v[220:223], v[28:31]
	v_mfma_f32_16x16x32_bf16 v[24:27], v[56:59], v[220:223], v[24:27]
	v_mfma_f32_16x16x32_bf16 v[12:15], v[48:51], v[240:243], v[12:15]
	v_mfma_f32_16x16x32_bf16 v[8:11], v[56:59], v[240:243], v[8:11]
	v_mfma_f32_16x16x32_bf16 v[76:79], v[52:55], v[208:211], v[76:79]
	v_mfma_f32_16x16x32_bf16 v[72:75], v[60:63], v[208:211], v[72:75]
	v_mfma_f32_16x16x32_bf16 v[44:47], v[52:55], v[216:219], v[44:47]
	v_mfma_f32_16x16x32_bf16 v[40:43], v[60:63], v[216:219], v[40:43]
	v_mfma_f32_16x16x32_bf16 v[28:31], v[52:55], v[224:227], v[28:31]
	v_mfma_f32_16x16x32_bf16 v[24:27], v[60:63], v[224:227], v[24:27]
	v_mfma_f32_16x16x32_bf16 v[12:15], v[52:55], v[244:247], v[12:15]
	v_mfma_f32_16x16x32_bf16 v[8:11], v[60:63], v[244:247], v[8:11]
	v_mfma_f32_16x16x32_bf16 v[36:39], v[164:167], v[212:215], v[36:39]
	v_mfma_f32_16x16x32_bf16 v[32:35], v[174:177], v[212:215], v[32:35]
	v_mfma_f32_16x16x32_bf16 v[20:23], v[164:167], v[220:223], v[20:23]
	v_mfma_f32_16x16x32_bf16 v[16:19], v[174:177], v[220:223], v[16:19]
	v_mfma_f32_16x16x32_bf16 v[4:7], v[164:167], v[240:243], v[4:7]
	v_mfma_f32_16x16x32_bf16 v[0:3], v[174:177], v[240:243], v[0:3]
	v_mfma_f32_16x16x32_bf16 v[48:51], v[164:167], v[204:207], v[68:71]
	v_mfma_f32_16x16x32_bf16 v[52:55], v[174:177], v[204:207], v[64:67]
	v_mfma_f32_16x16x32_bf16 v[36:39], v[170:173], v[216:219], v[36:39]
	v_mfma_f32_16x16x32_bf16 v[32:35], v[178:181], v[216:219], v[32:35]
	v_mfma_f32_16x16x32_bf16 v[20:23], v[170:173], v[224:227], v[20:23]
	v_mfma_f32_16x16x32_bf16 v[16:19], v[178:181], v[224:227], v[16:19]
	v_mfma_f32_16x16x32_bf16 v[4:7], v[170:173], v[244:247], v[4:7]
	v_mfma_f32_16x16x32_bf16 v[0:3], v[178:181], v[244:247], v[0:3]
	v_mfma_f32_16x16x32_bf16 v[48:51], v[170:173], v[208:211], v[48:51]
	v_mfma_f32_16x16x32_bf16 v[52:55], v[178:181], v[208:211], v[52:55]
	s_barrier
	s_setprio 0
	s_add_i32 s77, 0, 0x18000
	s_add_i32 s78, 0, 0x1c000
	v_add_u32_e32 v68, s77, v183
	v_add_u32_e32 v168, s78, v183
	ds_read_b128 v[56:59], v68
	ds_read_b128 v[60:63], v68 offset:1024
	ds_read_b128 v[64:67], v68 offset:2048
	ds_read_b128 v[68:71], v68 offset:3072
	ds_read_b128 v[164:167], v168
	ds_read_b128 v[170:173], v168 offset:1024
	ds_read_b128 v[174:177], v168 offset:2048
	ds_read_b128 v[178:181], v168 offset:3072
	s_add_u32 s58, s58, 0x40000
	s_addc_u32 s59, s59, 0
	s_mov_b32 m0, s66
	v_lshl_add_u64 v[236:237], s[58:59], 0, v[144:145]
	ds_read_b128 v[204:207], v202 offset:32768
	ds_read_b128 v[208:211], v202 offset:33792
	ds_read_b128 v[212:215], v202 offset:34816
	ds_read_b128 v[216:219], v202 offset:35840
	ds_read_b128 v[220:223], v202 offset:36864
	ds_read_b128 v[224:227], v202 offset:37888
	ds_read_b128 v[240:243], v202 offset:38912
	ds_read_b128 v[244:247], v202 offset:39936
	global_load_lds_dwordx4 v[236:237], off
	v_lshl_add_u64 v[236:237], s[58:59], 0, v[148:149]
	s_mov_b32 m0, s67
	s_nop 0
	global_load_lds_dwordx4 v[236:237], off
	s_waitcnt vmcnt(8)
	s_waitcnt lgkmcnt(0)
	s_setprio 1
	s_barrier
	v_mfma_f32_16x16x32_bf16 v[140:143], v[56:59], v[204:207], v[140:143]
	v_mfma_f32_16x16x32_bf16 v[136:139], v[64:67], v[204:207], v[136:139]
	v_mfma_f32_16x16x32_bf16 v[124:127], v[56:59], v[212:215], v[124:127]
	v_mfma_f32_16x16x32_bf16 v[120:123], v[64:67], v[212:215], v[120:123]
	v_mfma_f32_16x16x32_bf16 v[108:111], v[56:59], v[220:223], v[108:111]
	v_mfma_f32_16x16x32_bf16 v[104:107], v[64:67], v[220:223], v[104:107]
	v_mfma_f32_16x16x32_bf16 v[92:95], v[56:59], v[240:243], v[92:95]
	v_mfma_f32_16x16x32_bf16 v[88:91], v[64:67], v[240:243], v[88:91]
	v_mfma_f32_16x16x32_bf16 v[140:143], v[60:63], v[208:211], v[140:143]
	v_mfma_f32_16x16x32_bf16 v[136:139], v[68:71], v[208:211], v[136:139]
	v_mfma_f32_16x16x32_bf16 v[124:127], v[60:63], v[216:219], v[124:127]
	v_mfma_f32_16x16x32_bf16 v[120:123], v[68:71], v[216:219], v[120:123]
	v_mfma_f32_16x16x32_bf16 v[108:111], v[60:63], v[224:227], v[108:111]
	v_mfma_f32_16x16x32_bf16 v[104:107], v[68:71], v[224:227], v[104:107]
	v_mfma_f32_16x16x32_bf16 v[92:95], v[60:63], v[244:247], v[92:95]
	v_mfma_f32_16x16x32_bf16 v[88:91], v[68:71], v[244:247], v[88:91]
	v_mfma_f32_16x16x32_bf16 v[132:135], v[164:167], v[204:207], v[132:135]
	v_mfma_f32_16x16x32_bf16 v[128:131], v[174:177], v[204:207], v[128:131]
	v_mfma_f32_16x16x32_bf16 v[116:119], v[164:167], v[212:215], v[116:119]
	v_mfma_f32_16x16x32_bf16 v[112:115], v[174:177], v[212:215], v[112:115]
	v_mfma_f32_16x16x32_bf16 v[100:103], v[164:167], v[220:223], v[100:103]
	v_mfma_f32_16x16x32_bf16 v[96:99], v[174:177], v[220:223], v[96:99]
	v_mfma_f32_16x16x32_bf16 v[84:87], v[164:167], v[240:243], v[84:87]
	v_mfma_f32_16x16x32_bf16 v[80:83], v[174:177], v[240:243], v[80:83]
	v_mfma_f32_16x16x32_bf16 v[132:135], v[170:173], v[208:211], v[132:135]
	v_mfma_f32_16x16x32_bf16 v[128:131], v[178:181], v[208:211], v[128:131]
	v_mfma_f32_16x16x32_bf16 v[116:119], v[170:173], v[216:219], v[116:119]
	v_mfma_f32_16x16x32_bf16 v[112:115], v[178:181], v[216:219], v[112:115]
	v_mfma_f32_16x16x32_bf16 v[100:103], v[170:173], v[224:227], v[100:103]
	v_mfma_f32_16x16x32_bf16 v[96:99], v[178:181], v[224:227], v[96:99]
	v_mfma_f32_16x16x32_bf16 v[84:87], v[170:173], v[244:247], v[84:87]
	v_mfma_f32_16x16x32_bf16 v[80:83], v[178:181], v[244:247], v[80:83]
	s_barrier
	s_setprio 0
	s_add_i32 s58, s77, s62
	v_lshl_add_u64 v[228:229], v[228:229], 0, s[36:37]
	s_mov_b32 m0, s58
	ds_read_b128 v[204:207], v202 offset:49152
	ds_read_b128 v[208:211], v202 offset:50176
	ds_read_b128 v[212:215], v202 offset:51200
	ds_read_b128 v[216:219], v202 offset:52224
	ds_read_b128 v[220:223], v202 offset:53248
	ds_read_b128 v[224:227], v202 offset:54272
	ds_read_b128 v[240:243], v202 offset:55296
	ds_read_b128 v[244:247], v202 offset:56320
	global_load_lds_dwordx4 v[228:229], off
	s_add_i32 m0, s58, 0x2000
	s_add_u32 s20, s20, 0x40080
	v_lshl_add_u64 v[228:229], v[230:231], 0, s[36:37]
	s_addc_u32 s21, s21, 0
	s_add_i32 s58, s78, s62
	global_load_lds_dwordx4 v[228:229], off
	v_lshl_add_u64 v[228:229], s[20:21], 0, v[146:147]
	s_mov_b32 m0, s58
	s_nop 0
	global_load_lds_dwordx4 v[228:229], off
	v_lshl_add_u64 v[228:229], s[20:21], 0, v[150:151]
	s_add_i32 m0, s58, 0x2000
	s_nop 0
	global_load_lds_dwordx4 v[228:229], off
	v_lshl_add_u64 v[228:229], v[232:233], 0, s[36:37]
	s_mov_b32 m0, s69
	s_nop 0
	global_load_lds_dwordx4 v[228:229], off
	v_lshl_add_u64 v[228:229], v[234:235], 0, s[36:37]
	s_mov_b32 m0, s70
	s_nop 0
	global_load_lds_dwordx4 v[228:229], off
	s_waitcnt vmcnt(8)
	s_waitcnt lgkmcnt(0)
	s_setprio 1
	s_barrier
	v_mfma_f32_16x16x32_bf16 v[76:79], v[56:59], v[204:207], v[76:79]
	v_mfma_f32_16x16x32_bf16 v[72:75], v[64:67], v[204:207], v[72:75]
	v_mfma_f32_16x16x32_bf16 v[44:47], v[56:59], v[212:215], v[44:47]
	v_mfma_f32_16x16x32_bf16 v[40:43], v[64:67], v[212:215], v[40:43]
	v_mfma_f32_16x16x32_bf16 v[28:31], v[56:59], v[220:223], v[28:31]
	v_mfma_f32_16x16x32_bf16 v[24:27], v[64:67], v[220:223], v[24:27]
	v_mfma_f32_16x16x32_bf16 v[12:15], v[56:59], v[240:243], v[12:15]
	v_mfma_f32_16x16x32_bf16 v[8:11], v[64:67], v[240:243], v[8:11]
	v_mfma_f32_16x16x32_bf16 v[76:79], v[60:63], v[208:211], v[76:79]
	v_mfma_f32_16x16x32_bf16 v[72:75], v[68:71], v[208:211], v[72:75]
	v_mfma_f32_16x16x32_bf16 v[44:47], v[60:63], v[216:219], v[44:47]
	v_mfma_f32_16x16x32_bf16 v[40:43], v[68:71], v[216:219], v[40:43]
	v_mfma_f32_16x16x32_bf16 v[28:31], v[60:63], v[224:227], v[28:31]
	v_mfma_f32_16x16x32_bf16 v[24:27], v[68:71], v[224:227], v[24:27]
	v_mfma_f32_16x16x32_bf16 v[12:15], v[60:63], v[244:247], v[12:15]
	v_mfma_f32_16x16x32_bf16 v[8:11], v[68:71], v[244:247], v[8:11]
	v_mfma_f32_16x16x32_bf16 v[48:51], v[164:167], v[204:207], v[48:51]
	v_mfma_f32_16x16x32_bf16 v[68:71], v[170:173], v[208:211], v[48:51]
	v_mfma_f32_16x16x32_bf16 v[48:51], v[174:177], v[204:207], v[52:55]
	v_mfma_f32_16x16x32_bf16 v[36:39], v[164:167], v[212:215], v[36:39]
	v_mfma_f32_16x16x32_bf16 v[32:35], v[174:177], v[212:215], v[32:35]
	v_mfma_f32_16x16x32_bf16 v[20:23], v[164:167], v[220:223], v[20:23]
	v_mfma_f32_16x16x32_bf16 v[16:19], v[174:177], v[220:223], v[16:19]
	v_mfma_f32_16x16x32_bf16 v[4:7], v[164:167], v[240:243], v[4:7]
	v_mfma_f32_16x16x32_bf16 v[0:3], v[174:177], v[240:243], v[0:3]
	v_mfma_f32_16x16x32_bf16 v[64:67], v[178:181], v[208:211], v[48:51]
	v_mfma_f32_16x16x32_bf16 v[36:39], v[170:173], v[216:219], v[36:39]
	v_mfma_f32_16x16x32_bf16 v[32:35], v[178:181], v[216:219], v[32:35]
	v_mfma_f32_16x16x32_bf16 v[20:23], v[170:173], v[224:227], v[20:23]
	v_mfma_f32_16x16x32_bf16 v[16:19], v[178:181], v[224:227], v[16:19]
	v_mfma_f32_16x16x32_bf16 v[4:7], v[170:173], v[244:247], v[4:7]
	v_mfma_f32_16x16x32_bf16 v[0:3], v[178:181], v[244:247], v[0:3]
	s_barrier
	s_setprio 0
	s_add_i32 s76, s76, 2
	s_add_u32 s74, s74, 0x100
	s_addc_u32 s75, s75, 0
	s_add_u32 s40, s40, 0x100
	s_addc_u32 s41, s41, 0
	s_cmp_gt_u32 s76, 13
	s_cbranch_scc0 .LBB0_320
	s_and_b64 vcc, exec, s[42:43]
	s_cbranch_vccz .LBB0_323
	s_barrier

.LBB0_478:
	s_add_u32 s20, s40, 0xfffc0080
	s_addc_u32 s21, s41, -1
	s_add_i32 s65, 0, 0x10000
	s_cmp_eq_u32 s64, 12
	s_cselect_b32 s43, s15, s21
	s_cselect_b32 s42, s45, s20
	v_add_u32_e32 v167, s65, v149
	s_cselect_b32 s21, s13, s63
	s_cselect_b32 s20, s61, s62
	s_add_i32 s68, 0, 0x14000
	ds_read_b128 v[140:143], v167
	ds_read_b128 v[144:147], v167 offset:1024
	ds_read_b128 v[170:173], v167 offset:2048
	ds_read_b128 v[174:177], v167 offset:3072
	v_add_u32_e32 v167, s68, v149
	ds_read_b128 v[178:181], v167
	ds_read_b128 v[182:185], v167 offset:1024
	ds_read_b128 v[186:189], v167 offset:2048
	ds_read_b128 v[190:193], v167 offset:3072
	v_lshl_add_u64 v[226:227], s[40:41], 0, v[138:139]
	s_add_i32 m0, s53, 0xc000
	ds_read_b128 v[194:197], v166
	ds_read_b128 v[198:201], v166 offset:1024
	ds_read_b128 v[202:205], v166 offset:2048
	ds_read_b128 v[206:209], v166 offset:3072
	ds_read_b128 v[210:213], v166 offset:4096
	ds_read_b128 v[214:217], v166 offset:5120
	ds_read_b128 v[218:221], v166 offset:6144
	ds_read_b128 v[222:225], v166 offset:7168
	global_load_lds_dwordx4 v[226:227], off
	v_lshl_add_u64 v[226:227], s[40:41], 0, v[136:137]
	s_add_i32 m0, s53, 0xe000
	s_nop 0
	global_load_lds_dwordx4 v[226:227], off
	s_waitcnt vmcnt(8)
	s_waitcnt lgkmcnt(0)
	s_setprio 1
	s_barrier
	v_mfma_f32_16x16x32_bf16 v[124:127], v[140:143], v[194:197], v[124:127]
	v_mfma_f32_16x16x32_bf16 v[120:123], v[170:173], v[194:197], v[120:123]
	v_mfma_f32_16x16x32_bf16 v[108:111], v[140:143], v[202:205], v[108:111]
	v_mfma_f32_16x16x32_bf16 v[104:107], v[170:173], v[202:205], v[104:107]
	v_mfma_f32_16x16x32_bf16 v[92:95], v[140:143], v[210:213], v[92:95]
	v_mfma_f32_16x16x32_bf16 v[88:91], v[170:173], v[210:213], v[88:91]
	v_mfma_f32_16x16x32_bf16 v[76:79], v[140:143], v[218:221], v[76:79]
	v_mfma_f32_16x16x32_bf16 v[72:75], v[170:173], v[218:221], v[72:75]
	v_mfma_f32_16x16x32_bf16 v[124:127], v[144:147], v[198:201], v[124:127]
	v_mfma_f32_16x16x32_bf16 v[120:123], v[174:177], v[198:201], v[120:123]
	v_mfma_f32_16x16x32_bf16 v[108:111], v[144:147], v[206:209], v[108:111]
	v_mfma_f32_16x16x32_bf16 v[104:107], v[174:177], v[206:209], v[104:107]
	v_mfma_f32_16x16x32_bf16 v[92:95], v[144:147], v[214:217], v[92:95]
	v_mfma_f32_16x16x32_bf16 v[88:91], v[174:177], v[214:217], v[88:91]
	v_mfma_f32_16x16x32_bf16 v[76:79], v[144:147], v[222:225], v[76:79]
	v_mfma_f32_16x16x32_bf16 v[72:75], v[174:177], v[222:225], v[72:75]
	v_mfma_f32_16x16x32_bf16 v[116:119], v[178:181], v[194:197], v[116:119]
	v_mfma_f32_16x16x32_bf16 v[112:115], v[186:189], v[194:197], v[112:115]
	v_mfma_f32_16x16x32_bf16 v[100:103], v[178:181], v[202:205], v[100:103]
	v_mfma_f32_16x16x32_bf16 v[96:99], v[186:189], v[202:205], v[96:99]
	v_mfma_f32_16x16x32_bf16 v[84:87], v[178:181], v[210:213], v[84:87]
	v_mfma_f32_16x16x32_bf16 v[80:83], v[186:189], v[210:213], v[80:83]
	v_mfma_f32_16x16x32_bf16 v[68:71], v[178:181], v[218:221], v[68:71]
	v_mfma_f32_16x16x32_bf16 v[64:67], v[186:189], v[218:221], v[64:67]
	v_mfma_f32_16x16x32_bf16 v[116:119], v[182:185], v[198:201], v[116:119]
	v_mfma_f32_16x16x32_bf16 v[112:115], v[190:193], v[198:201], v[112:115]
	v_mfma_f32_16x16x32_bf16 v[100:103], v[182:185], v[206:209], v[100:103]
	v_mfma_f32_16x16x32_bf16 v[96:99], v[190:193], v[206:209], v[96:99]
	v_mfma_f32_16x16x32_bf16 v[84:87], v[182:185], v[214:217], v[84:87]
	v_mfma_f32_16x16x32_bf16 v[80:83], v[190:193], v[214:217], v[80:83]
	v_mfma_f32_16x16x32_bf16 v[68:71], v[182:185], v[222:225], v[68:71]
	v_mfma_f32_16x16x32_bf16 v[64:67], v[190:193], v[222:225], v[64:67]
	s_barrier
	s_setprio 0
	s_add_i32 s65, s65, s50
	v_lshl_add_u64 v[226:227], s[20:21], 0, v[132:133]
	s_mov_b32 m0, s65
	ds_read_b128 v[194:197], v166 offset:16384
	ds_read_b128 v[198:201], v166 offset:17408
	ds_read_b128 v[202:205], v166 offset:18432
	ds_read_b128 v[206:209], v166 offset:19456
	ds_read_b128 v[210:213], v166 offset:20480
	ds_read_b128 v[214:217], v166 offset:21504
	ds_read_b128 v[218:221], v166 offset:22528
	ds_read_b128 v[222:225], v166 offset:23552
	global_load_lds_dwordx4 v[226:227], off
	s_add_i32 m0, s65, 0x2000
	s_add_u32 s66, s20, 0x40000
	v_lshl_add_u64 v[228:229], s[20:21], 0, v[128:129]
	s_addc_u32 s67, s21, 0
	s_add_i32 s65, s68, s50
	global_load_lds_dwordx4 v[228:229], off
	v_lshl_add_u64 v[230:231], s[66:67], 0, v[132:133]
	s_mov_b32 m0, s65
	v_lshl_add_u64 v[232:233], s[42:43], 0, v[130:131]
	global_load_lds_dwordx4 v[230:231], off
	v_lshl_add_u64 v[230:231], s[66:67], 0, v[128:129]
	s_add_i32 m0, s65, 0x2000
	s_nop 0
	global_load_lds_dwordx4 v[230:231], off
	v_lshl_add_u64 v[230:231], s[42:43], 0, v[134:135]
	s_mov_b32 m0, s53
	s_nop 0
	global_load_lds_dwordx4 v[230:231], off
	s_mov_b32 m0, s54
	s_nop 0
	global_load_lds_dwordx4 v[232:233], off
	s_waitcnt vmcnt(8)
	s_waitcnt lgkmcnt(0)
	s_setprio 1
	s_barrier
	v_mfma_f32_16x16x32_bf16 v[60:63], v[140:143], v[194:197], v[60:63]
	v_mfma_f32_16x16x32_bf16 v[56:59], v[170:173], v[194:197], v[56:59]
	v_mfma_f32_16x16x32_bf16 v[44:47], v[140:143], v[202:205], v[44:47]
	v_mfma_f32_16x16x32_bf16 v[40:43], v[170:173], v[202:205], v[40:43]
	v_mfma_f32_16x16x32_bf16 v[28:31], v[140:143], v[210:213], v[28:31]
	v_mfma_f32_16x16x32_bf16 v[24:27], v[170:173], v[210:213], v[24:27]
	v_mfma_f32_16x16x32_bf16 v[12:15], v[140:143], v[218:221], v[12:15]
	v_mfma_f32_16x16x32_bf16 v[8:11], v[170:173], v[218:221], v[8:11]
	v_mfma_f32_16x16x32_bf16 v[60:63], v[144:147], v[198:201], v[60:63]
	v_mfma_f32_16x16x32_bf16 v[56:59], v[174:177], v[198:201], v[56:59]
	v_mfma_f32_16x16x32_bf16 v[44:47], v[144:147], v[206:209], v[44:47]
	v_mfma_f32_16x16x32_bf16 v[40:43], v[174:177], v[206:209], v[40:43]
	v_mfma_f32_16x16x32_bf16 v[28:31], v[144:147], v[214:217], v[28:31]
	v_mfma_f32_16x16x32_bf16 v[24:27], v[174:177], v[214:217], v[24:27]
	v_mfma_f32_16x16x32_bf16 v[12:15], v[144:147], v[222:225], v[12:15]
	v_mfma_f32_16x16x32_bf16 v[8:11], v[174:177], v[222:225], v[8:11]
	v_mfma_f32_16x16x32_bf16 v[52:55], v[178:181], v[194:197], v[52:55]
	v_mfma_f32_16x16x32_bf16 v[48:51], v[186:189], v[194:197], v[48:51]
	v_mfma_f32_16x16x32_bf16 v[36:39], v[178:181], v[202:205], v[36:39]
	v_mfma_f32_16x16x32_bf16 v[32:35], v[186:189], v[202:205], v[32:35]
	v_mfma_f32_16x16x32_bf16 v[20:23], v[178:181], v[210:213], v[20:23]
	v_mfma_f32_16x16x32_bf16 v[16:19], v[186:189], v[210:213], v[16:19]
	v_mfma_f32_16x16x32_bf16 v[4:7], v[178:181], v[218:221], v[4:7]
	v_mfma_f32_16x16x32_bf16 v[0:3], v[186:189], v[218:221], v[0:3]
	v_mfma_f32_16x16x32_bf16 v[52:55], v[182:185], v[198:201], v[52:55]
	v_mfma_f32_16x16x32_bf16 v[48:51], v[190:193], v[198:201], v[48:51]
	v_mfma_f32_16x16x32_bf16 v[36:39], v[182:185], v[206:209], v[36:39]
	v_mfma_f32_16x16x32_bf16 v[32:35], v[190:193], v[206:209], v[32:35]
	v_mfma_f32_16x16x32_bf16 v[20:23], v[182:185], v[214:217], v[20:23]
	v_mfma_f32_16x16x32_bf16 v[16:19], v[190:193], v[214:217], v[16:19]
	v_mfma_f32_16x16x32_bf16 v[4:7], v[182:185], v[222:225], v[4:7]
	v_mfma_f32_16x16x32_bf16 v[0:3], v[190:193], v[222:225], v[0:3]
	s_barrier
	s_setprio 0
	s_add_i32 s65, 0, 0x18000
	v_add_u32_e32 v167, s65, v149
	s_add_i32 s66, 0, 0x1c000
	ds_read_b128 v[140:143], v167
	ds_read_b128 v[144:147], v167 offset:1024
	ds_read_b128 v[170:173], v167 offset:2048
	ds_read_b128 v[174:177], v167 offset:3072
	v_add_u32_e32 v167, s66, v149
	ds_read_b128 v[178:181], v167
	ds_read_b128 v[182:185], v167 offset:1024
	ds_read_b128 v[186:189], v167 offset:2048
	ds_read_b128 v[190:193], v167 offset:3072
	s_add_u32 s42, s42, 0x40000
	s_addc_u32 s43, s43, 0
	s_mov_b32 m0, s55
	v_lshl_add_u64 v[234:235], s[42:43], 0, v[134:135]
	ds_read_b128 v[194:197], v166 offset:32768
	ds_read_b128 v[198:201], v166 offset:33792
	ds_read_b128 v[202:205], v166 offset:34816
	ds_read_b128 v[206:209], v166 offset:35840
	ds_read_b128 v[210:213], v166 offset:36864
	ds_read_b128 v[214:217], v166 offset:37888
	ds_read_b128 v[218:221], v166 offset:38912
	ds_read_b128 v[222:225], v166 offset:39936
	global_load_lds_dwordx4 v[234:235], off
	v_lshl_add_u64 v[234:235], s[42:43], 0, v[130:131]
	s_mov_b32 m0, s56
	s_nop 0
	global_load_lds_dwordx4 v[234:235], off
	s_waitcnt vmcnt(8)
	s_waitcnt lgkmcnt(0)
	s_setprio 1
	s_barrier
	v_mfma_f32_16x16x32_bf16 v[124:127], v[140:143], v[194:197], v[124:127]
	v_mfma_f32_16x16x32_bf16 v[120:123], v[170:173], v[194:197], v[120:123]
	v_mfma_f32_16x16x32_bf16 v[108:111], v[140:143], v[202:205], v[108:111]
	v_mfma_f32_16x16x32_bf16 v[104:107], v[170:173], v[202:205], v[104:107]
	v_mfma_f32_16x16x32_bf16 v[92:95], v[140:143], v[210:213], v[92:95]
	v_mfma_f32_16x16x32_bf16 v[88:91], v[170:173], v[210:213], v[88:91]
	v_mfma_f32_16x16x32_bf16 v[76:79], v[140:143], v[218:221], v[76:79]
	v_mfma_f32_16x16x32_bf16 v[72:75], v[170:173], v[218:221], v[72:75]
	v_mfma_f32_16x16x32_bf16 v[124:127], v[144:147], v[198:201], v[124:127]
	v_mfma_f32_16x16x32_bf16 v[120:123], v[174:177], v[198:201], v[120:123]
	v_mfma_f32_16x16x32_bf16 v[108:111], v[144:147], v[206:209], v[108:111]
	v_mfma_f32_16x16x32_bf16 v[104:107], v[174:177], v[206:209], v[104:107]
	v_mfma_f32_16x16x32_bf16 v[92:95], v[144:147], v[214:217], v[92:95]
	v_mfma_f32_16x16x32_bf16 v[88:91], v[174:177], v[214:217], v[88:91]
	v_mfma_f32_16x16x32_bf16 v[76:79], v[144:147], v[222:225], v[76:79]
	v_mfma_f32_16x16x32_bf16 v[72:75], v[174:177], v[222:225], v[72:75]
	v_mfma_f32_16x16x32_bf16 v[116:119], v[178:181], v[194:197], v[116:119]
	v_mfma_f32_16x16x32_bf16 v[112:115], v[186:189], v[194:197], v[112:115]
	v_mfma_f32_16x16x32_bf16 v[100:103], v[178:181], v[202:205], v[100:103]
	v_mfma_f32_16x16x32_bf16 v[96:99], v[186:189], v[202:205], v[96:99]
	v_mfma_f32_16x16x32_bf16 v[84:87], v[178:181], v[210:213], v[84:87]
	v_mfma_f32_16x16x32_bf16 v[80:83], v[186:189], v[210:213], v[80:83]
	v_mfma_f32_16x16x32_bf16 v[68:71], v[178:181], v[218:221], v[68:71]
	v_mfma_f32_16x16x32_bf16 v[64:67], v[186:189], v[218:221], v[64:67]
	v_mfma_f32_16x16x32_bf16 v[116:119], v[182:185], v[198:201], v[116:119]
	v_mfma_f32_16x16x32_bf16 v[112:115], v[190:193], v[198:201], v[112:115]
	v_mfma_f32_16x16x32_bf16 v[100:103], v[182:185], v[206:209], v[100:103]
	v_mfma_f32_16x16x32_bf16 v[96:99], v[190:193], v[206:209], v[96:99]
	v_mfma_f32_16x16x32_bf16 v[84:87], v[182:185], v[214:217], v[84:87]
	v_mfma_f32_16x16x32_bf16 v[80:83], v[190:193], v[214:217], v[80:83]
	v_mfma_f32_16x16x32_bf16 v[68:71], v[182:185], v[222:225], v[68:71]
	v_mfma_f32_16x16x32_bf16 v[64:67], v[190:193], v[222:225], v[64:67]
	s_barrier
	s_setprio 0
	s_add_i32 s42, s65, s50
	v_lshl_add_u64 v[226:227], v[226:227], 0, s[36:37]
	s_mov_b32 m0, s42
	ds_read_b128 v[194:197], v166 offset:49152
	ds_read_b128 v[198:201], v166 offset:50176
	ds_read_b128 v[202:205], v166 offset:51200
	ds_read_b128 v[206:209], v166 offset:52224
	ds_read_b128 v[210:213], v166 offset:53248
	ds_read_b128 v[214:217], v166 offset:54272
	ds_read_b128 v[218:221], v166 offset:55296
	ds_read_b128 v[222:225], v166 offset:56320
	global_load_lds_dwordx4 v[226:227], off
	s_add_i32 m0, s42, 0x2000
	s_add_u32 s20, s20, 0x40080
	v_lshl_add_u64 v[226:227], v[228:229], 0, s[36:37]
	s_addc_u32 s21, s21, 0
	s_add_i32 s42, s66, s50
	global_load_lds_dwordx4 v[226:227], off
	v_lshl_add_u64 v[226:227], s[20:21], 0, v[132:133]
	s_mov_b32 m0, s42
	s_nop 0
	global_load_lds_dwordx4 v[226:227], off
	v_lshl_add_u64 v[226:227], s[20:21], 0, v[128:129]
	s_add_i32 m0, s42, 0x2000
	s_nop 0
	global_load_lds_dwordx4 v[226:227], off
	v_lshl_add_u64 v[226:227], v[230:231], 0, s[36:37]
	s_mov_b32 m0, s57
	s_nop 0
	global_load_lds_dwordx4 v[226:227], off
	v_lshl_add_u64 v[226:227], v[232:233], 0, s[36:37]
	s_mov_b32 m0, s58
	s_nop 0
	global_load_lds_dwordx4 v[226:227], off
	s_waitcnt vmcnt(8)
	s_waitcnt lgkmcnt(0)
	s_setprio 1
	s_barrier
	v_mfma_f32_16x16x32_bf16 v[60:63], v[140:143], v[194:197], v[60:63]
	v_mfma_f32_16x16x32_bf16 v[56:59], v[170:173], v[194:197], v[56:59]
	v_mfma_f32_16x16x32_bf16 v[44:47], v[140:143], v[202:205], v[44:47]
	v_mfma_f32_16x16x32_bf16 v[40:43], v[170:173], v[202:205], v[40:43]
	v_mfma_f32_16x16x32_bf16 v[28:31], v[140:143], v[210:213], v[28:31]
	v_mfma_f32_16x16x32_bf16 v[24:27], v[170:173], v[210:213], v[24:27]
	v_mfma_f32_16x16x32_bf16 v[12:15], v[140:143], v[218:221], v[12:15]
	v_mfma_f32_16x16x32_bf16 v[8:11], v[170:173], v[218:221], v[8:11]
	v_mfma_f32_16x16x32_bf16 v[60:63], v[144:147], v[198:201], v[60:63]
	v_mfma_f32_16x16x32_bf16 v[56:59], v[174:177], v[198:201], v[56:59]
	v_mfma_f32_16x16x32_bf16 v[44:47], v[144:147], v[206:209], v[44:47]
	v_mfma_f32_16x16x32_bf16 v[40:43], v[174:177], v[206:209], v[40:43]
	v_mfma_f32_16x16x32_bf16 v[28:31], v[144:147], v[214:217], v[28:31]
	v_mfma_f32_16x16x32_bf16 v[24:27], v[174:177], v[214:217], v[24:27]
	v_mfma_f32_16x16x32_bf16 v[12:15], v[144:147], v[222:225], v[12:15]
	v_mfma_f32_16x16x32_bf16 v[8:11], v[174:177], v[222:225], v[8:11]
	v_mfma_f32_16x16x32_bf16 v[52:55], v[178:181], v[194:197], v[52:55]
	v_mfma_f32_16x16x32_bf16 v[48:51], v[186:189], v[194:197], v[48:51]
	v_mfma_f32_16x16x32_bf16 v[36:39], v[178:181], v[202:205], v[36:39]
	v_mfma_f32_16x16x32_bf16 v[32:35], v[186:189], v[202:205], v[32:35]
	v_mfma_f32_16x16x32_bf16 v[20:23], v[178:181], v[210:213], v[20:23]
	v_mfma_f32_16x16x32_bf16 v[16:19], v[186:189], v[210:213], v[16:19]
	v_mfma_f32_16x16x32_bf16 v[4:7], v[178:181], v[218:221], v[4:7]
	v_mfma_f32_16x16x32_bf16 v[0:3], v[186:189], v[218:221], v[0:3]
	v_mfma_f32_16x16x32_bf16 v[52:55], v[182:185], v[198:201], v[52:55]
	v_mfma_f32_16x16x32_bf16 v[48:51], v[190:193], v[198:201], v[48:51]
	v_mfma_f32_16x16x32_bf16 v[36:39], v[182:185], v[206:209], v[36:39]
	v_mfma_f32_16x16x32_bf16 v[32:35], v[190:193], v[206:209], v[32:35]
	v_mfma_f32_16x16x32_bf16 v[20:23], v[182:185], v[214:217], v[20:23]
	v_mfma_f32_16x16x32_bf16 v[16:19], v[190:193], v[214:217], v[16:19]
	v_mfma_f32_16x16x32_bf16 v[4:7], v[182:185], v[222:225], v[4:7]
	v_mfma_f32_16x16x32_bf16 v[0:3], v[190:193], v[222:225], v[0:3]
	s_barrier
	s_setprio 0
	s_add_i32 s64, s64, 2
	s_add_u32 s62, s62, 0x100
	s_addc_u32 s63, s63, 0
	s_add_u32 s40, s40, 0x100
	s_addc_u32 s41, s41, 0
	s_cmp_gt_u32 s64, 13
	s_cbranch_scc0 .LBB0_478
	s_and_b64 vcc, exec, s[8:9]
	s_cbranch_vccz .LBB0_481
	s_barrier

.LBB0_575:
	s_add_i32 s54, s20, 2
	s_add_u32 s55, s42, 0x80
	s_addc_u32 s21, s43, 0
	s_add_i32 s74, 0, 0x10000
	s_cmp_eq_u32 s31, s20
	s_cselect_b32 s21, s51, s21
	s_cselect_b32 s20, s50, s55
	s_cselect_b32 s73, s53, s45
	s_cselect_b32 s72, s52, s44
	s_add_i32 s55, 0, 0x14000
	v_add_u32_e32 v124, s74, v207
	v_add_u32_e32 v166, s55, v207
	ds_read_b128 v[88:91], v124
	ds_read_b128 v[100:103], v124 offset:1024
	ds_read_b128 v[112:115], v124 offset:2048
	ds_read_b128 v[124:127], v124 offset:3072
	ds_read_b128 v[136:139], v166
	ds_read_b128 v[148:151], v166 offset:1024
	ds_read_b128 v[152:155], v166 offset:2048
	ds_read_b128 v[170:173], v166 offset:3072
	v_lshl_add_u64 v[166:167], s[42:43], 0, v[164:165]
	s_add_i32 m0, s61, 0xc000
	ds_read_b128 v[174:177], v211
	ds_read_b128 v[178:181], v211 offset:1024
	ds_read_b128 v[182:185], v211 offset:2048
	ds_read_b128 v[186:189], v211 offset:3072
	ds_read_b128 v[190:193], v211 offset:4096
	ds_read_b128 v[194:197], v211 offset:5120
	ds_read_b128 v[198:201], v211 offset:6144
	ds_read_b128 v[202:205], v211 offset:7168
	global_load_lds_dwordx4 v[166:167], off
	v_lshl_add_u64 v[166:167], s[42:43], 0, v[162:163]
	s_add_i32 m0, s61, 0xe000
	s_nop 0
	global_load_lds_dwordx4 v[166:167], off
	s_waitcnt vmcnt(8)
	s_waitcnt lgkmcnt(0)
	s_setprio 1
	s_barrier
	v_mfma_f32_16x16x32_bf16 v[144:147], v[88:91], v[174:177], v[144:147]
	v_mfma_f32_16x16x32_bf16 v[140:143], v[112:115], v[174:177], v[140:143]
	v_mfma_f32_16x16x32_bf16 v[120:123], v[88:91], v[182:185], v[120:123]
	v_mfma_f32_16x16x32_bf16 v[116:119], v[112:115], v[182:185], v[116:119]
	v_mfma_f32_16x16x32_bf16 v[96:99], v[88:91], v[190:193], v[96:99]
	v_mfma_f32_16x16x32_bf16 v[92:95], v[112:115], v[190:193], v[92:95]
	v_mfma_f32_16x16x32_bf16 v[76:79], v[88:91], v[198:201], v[76:79]
	v_mfma_f32_16x16x32_bf16 v[72:75], v[112:115], v[198:201], v[72:75]
	v_mfma_f32_16x16x32_bf16 v[144:147], v[100:103], v[178:181], v[144:147]
	v_mfma_f32_16x16x32_bf16 v[140:143], v[124:127], v[178:181], v[140:143]
	v_mfma_f32_16x16x32_bf16 v[120:123], v[100:103], v[186:189], v[120:123]
	v_mfma_f32_16x16x32_bf16 v[116:119], v[124:127], v[186:189], v[116:119]
	v_mfma_f32_16x16x32_bf16 v[96:99], v[100:103], v[194:197], v[96:99]
	v_mfma_f32_16x16x32_bf16 v[92:95], v[124:127], v[194:197], v[92:95]
	v_mfma_f32_16x16x32_bf16 v[76:79], v[100:103], v[202:205], v[76:79]
	v_mfma_f32_16x16x32_bf16 v[72:75], v[124:127], v[202:205], v[72:75]
	v_mfma_f32_16x16x32_bf16 v[132:135], v[136:139], v[174:177], v[132:135]
	v_mfma_f32_16x16x32_bf16 v[128:131], v[152:155], v[174:177], v[128:131]
	v_mfma_f32_16x16x32_bf16 v[108:111], v[136:139], v[182:185], v[108:111]
	v_mfma_f32_16x16x32_bf16 v[104:107], v[152:155], v[182:185], v[104:107]
	v_mfma_f32_16x16x32_bf16 v[84:87], v[136:139], v[190:193], v[84:87]
	v_mfma_f32_16x16x32_bf16 v[80:83], v[152:155], v[190:193], v[80:83]
	v_mfma_f32_16x16x32_bf16 v[68:71], v[136:139], v[198:201], v[68:71]
	v_mfma_f32_16x16x32_bf16 v[64:67], v[152:155], v[198:201], v[64:67]
	v_mfma_f32_16x16x32_bf16 v[132:135], v[148:151], v[178:181], v[132:135]
	v_mfma_f32_16x16x32_bf16 v[128:131], v[170:173], v[178:181], v[128:131]
	v_mfma_f32_16x16x32_bf16 v[108:111], v[148:151], v[186:189], v[108:111]
	v_mfma_f32_16x16x32_bf16 v[104:107], v[170:173], v[186:189], v[104:107]
	v_mfma_f32_16x16x32_bf16 v[84:87], v[148:151], v[194:197], v[84:87]
	v_mfma_f32_16x16x32_bf16 v[80:83], v[170:173], v[194:197], v[80:83]
	v_mfma_f32_16x16x32_bf16 v[68:71], v[148:151], v[202:205], v[68:71]
	v_mfma_f32_16x16x32_bf16 v[64:67], v[170:173], v[202:205], v[64:67]
	s_barrier
	s_setprio 0
	s_add_i32 s74, s74, s56
	v_lshl_add_u64 v[166:167], s[72:73], 0, v[168:169]
	s_mov_b32 m0, s74
	ds_read_b128 v[174:177], v211 offset:16384
	ds_read_b128 v[178:181], v211 offset:17408
	ds_read_b128 v[182:185], v211 offset:18432
	ds_read_b128 v[186:189], v211 offset:19456
	ds_read_b128 v[190:193], v211 offset:20480
	ds_read_b128 v[194:197], v211 offset:21504
	ds_read_b128 v[198:201], v211 offset:22528
	ds_read_b128 v[202:205], v211 offset:23552
	global_load_lds_dwordx4 v[166:167], off
	s_add_i32 m0, s74, 0x2000
	v_lshl_add_u64 v[212:213], s[72:73], 0, v[156:157]
	s_add_u32 s72, s72, s0
	s_addc_u32 s73, s73, 0
	s_add_i32 s55, s55, s56
	global_load_lds_dwordx4 v[212:213], off
	v_lshl_add_u64 v[214:215], s[72:73], 0, v[168:169]
	s_mov_b32 m0, s55
	v_lshl_add_u64 v[216:217], s[72:73], 0, v[156:157]
	global_load_lds_dwordx4 v[214:215], off
	s_add_i32 m0, s55, 0x2000
	v_lshl_add_u64 v[218:219], s[20:21], 0, v[160:161]
	global_load_lds_dwordx4 v[216:217], off
	s_mov_b32 m0, s61
	v_lshl_add_u64 v[220:221], s[20:21], 0, v[158:159]
	global_load_lds_dwordx4 v[218:219], off
	s_mov_b32 m0, s62
	s_nop 0
	global_load_lds_dwordx4 v[220:221], off
	s_waitcnt vmcnt(8)
	s_waitcnt lgkmcnt(0)
	s_setprio 1
	s_barrier
	v_mfma_f32_16x16x32_bf16 v[60:63], v[88:91], v[174:177], v[60:63]
	v_mfma_f32_16x16x32_bf16 v[56:59], v[112:115], v[174:177], v[56:59]
	v_mfma_f32_16x16x32_bf16 v[44:47], v[88:91], v[182:185], v[44:47]
	v_mfma_f32_16x16x32_bf16 v[40:43], v[112:115], v[182:185], v[40:43]
	v_mfma_f32_16x16x32_bf16 v[28:31], v[88:91], v[190:193], v[28:31]
	v_mfma_f32_16x16x32_bf16 v[24:27], v[112:115], v[190:193], v[24:27]
	v_mfma_f32_16x16x32_bf16 v[12:15], v[88:91], v[198:201], v[12:15]
	v_mfma_f32_16x16x32_bf16 v[8:11], v[112:115], v[198:201], v[8:11]
	v_mfma_f32_16x16x32_bf16 v[60:63], v[100:103], v[178:181], v[60:63]
	v_mfma_f32_16x16x32_bf16 v[56:59], v[124:127], v[178:181], v[56:59]
	v_mfma_f32_16x16x32_bf16 v[44:47], v[100:103], v[186:189], v[44:47]
	v_mfma_f32_16x16x32_bf16 v[40:43], v[124:127], v[186:189], v[40:43]
	v_mfma_f32_16x16x32_bf16 v[28:31], v[100:103], v[194:197], v[28:31]
	v_mfma_f32_16x16x32_bf16 v[24:27], v[124:127], v[194:197], v[24:27]
	v_mfma_f32_16x16x32_bf16 v[12:15], v[100:103], v[202:205], v[12:15]
	v_mfma_f32_16x16x32_bf16 v[8:11], v[124:127], v[202:205], v[8:11]
	v_mfma_f32_16x16x32_bf16 v[52:55], v[136:139], v[174:177], v[52:55]
	v_mfma_f32_16x16x32_bf16 v[48:51], v[152:155], v[174:177], v[48:51]
	v_mfma_f32_16x16x32_bf16 v[36:39], v[136:139], v[182:185], v[36:39]
	v_mfma_f32_16x16x32_bf16 v[32:35], v[152:155], v[182:185], v[32:35]
	v_mfma_f32_16x16x32_bf16 v[20:23], v[136:139], v[190:193], v[20:23]
	v_mfma_f32_16x16x32_bf16 v[16:19], v[152:155], v[190:193], v[16:19]
	v_mfma_f32_16x16x32_bf16 v[4:7], v[136:139], v[198:201], v[4:7]
	v_mfma_f32_16x16x32_bf16 v[0:3], v[152:155], v[198:201], v[0:3]
	v_mfma_f32_16x16x32_bf16 v[52:55], v[148:151], v[178:181], v[52:55]
	v_mfma_f32_16x16x32_bf16 v[48:51], v[170:173], v[178:181], v[48:51]
	v_mfma_f32_16x16x32_bf16 v[36:39], v[148:151], v[186:189], v[36:39]
	v_mfma_f32_16x16x32_bf16 v[32:35], v[170:173], v[186:189], v[32:35]
	v_mfma_f32_16x16x32_bf16 v[20:23], v[148:151], v[194:197], v[20:23]
	v_mfma_f32_16x16x32_bf16 v[16:19], v[170:173], v[194:197], v[16:19]
	v_mfma_f32_16x16x32_bf16 v[4:7], v[148:151], v[202:205], v[4:7]
	v_mfma_f32_16x16x32_bf16 v[0:3], v[170:173], v[202:205], v[0:3]
	s_barrier
	s_setprio 0
	s_add_i32 s55, 0, 0x18000
	s_add_i32 s72, 0, 0x1c000
	v_add_u32_e32 v124, s55, v207
	v_add_u32_e32 v170, s72, v207
	ds_read_b128 v[88:91], v124
	ds_read_b128 v[100:103], v124 offset:1024
	ds_read_b128 v[112:115], v124 offset:2048
	ds_read_b128 v[124:127], v124 offset:3072
	ds_read_b128 v[136:139], v170
	ds_read_b128 v[148:151], v170 offset:1024
	ds_read_b128 v[152:155], v170 offset:2048
	ds_read_b128 v[170:173], v170 offset:3072
	s_add_u32 s20, s20, s0
	s_addc_u32 s21, s21, 0
	s_mov_b32 m0, s63
	v_lshl_add_u64 v[222:223], s[20:21], 0, v[160:161]
	ds_read_b128 v[174:177], v211 offset:32768
	ds_read_b128 v[178:181], v211 offset:33792
	ds_read_b128 v[182:185], v211 offset:34816
	ds_read_b128 v[186:189], v211 offset:35840
	ds_read_b128 v[190:193], v211 offset:36864
	ds_read_b128 v[194:197], v211 offset:37888
	ds_read_b128 v[198:201], v211 offset:38912
	ds_read_b128 v[202:205], v211 offset:39936
	global_load_lds_dwordx4 v[222:223], off
	v_lshl_add_u64 v[222:223], s[20:21], 0, v[158:159]
	s_mov_b32 m0, s64
	s_nop 0
	global_load_lds_dwordx4 v[222:223], off
	s_waitcnt vmcnt(8)
	s_waitcnt lgkmcnt(0)
	s_setprio 1
	s_barrier
	v_mfma_f32_16x16x32_bf16 v[144:147], v[88:91], v[174:177], v[144:147]
	v_mfma_f32_16x16x32_bf16 v[140:143], v[112:115], v[174:177], v[140:143]
	v_mfma_f32_16x16x32_bf16 v[120:123], v[88:91], v[182:185], v[120:123]
	v_mfma_f32_16x16x32_bf16 v[116:119], v[112:115], v[182:185], v[116:119]
	v_mfma_f32_16x16x32_bf16 v[96:99], v[88:91], v[190:193], v[96:99]
	v_mfma_f32_16x16x32_bf16 v[92:95], v[112:115], v[190:193], v[92:95]
	v_mfma_f32_16x16x32_bf16 v[76:79], v[88:91], v[198:201], v[76:79]
	v_mfma_f32_16x16x32_bf16 v[72:75], v[112:115], v[198:201], v[72:75]
	v_mfma_f32_16x16x32_bf16 v[144:147], v[100:103], v[178:181], v[144:147]
	v_mfma_f32_16x16x32_bf16 v[140:143], v[124:127], v[178:181], v[140:143]
	v_mfma_f32_16x16x32_bf16 v[120:123], v[100:103], v[186:189], v[120:123]
	v_mfma_f32_16x16x32_bf16 v[116:119], v[124:127], v[186:189], v[116:119]
	v_mfma_f32_16x16x32_bf16 v[96:99], v[100:103], v[194:197], v[96:99]
	v_mfma_f32_16x16x32_bf16 v[92:95], v[124:127], v[194:197], v[92:95]
	v_mfma_f32_16x16x32_bf16 v[76:79], v[100:103], v[202:205], v[76:79]
	v_mfma_f32_16x16x32_bf16 v[72:75], v[124:127], v[202:205], v[72:75]
	v_mfma_f32_16x16x32_bf16 v[132:135], v[136:139], v[174:177], v[132:135]
	v_mfma_f32_16x16x32_bf16 v[128:131], v[152:155], v[174:177], v[128:131]
	v_mfma_f32_16x16x32_bf16 v[108:111], v[136:139], v[182:185], v[108:111]
	v_mfma_f32_16x16x32_bf16 v[104:107], v[152:155], v[182:185], v[104:107]
	v_mfma_f32_16x16x32_bf16 v[84:87], v[136:139], v[190:193], v[84:87]
	v_mfma_f32_16x16x32_bf16 v[80:83], v[152:155], v[190:193], v[80:83]
	v_mfma_f32_16x16x32_bf16 v[68:71], v[136:139], v[198:201], v[68:71]
	v_mfma_f32_16x16x32_bf16 v[64:67], v[152:155], v[198:201], v[64:67]
	v_mfma_f32_16x16x32_bf16 v[132:135], v[148:151], v[178:181], v[132:135]
	v_mfma_f32_16x16x32_bf16 v[128:131], v[170:173], v[178:181], v[128:131]
	v_mfma_f32_16x16x32_bf16 v[108:111], v[148:151], v[186:189], v[108:111]
	v_mfma_f32_16x16x32_bf16 v[104:107], v[170:173], v[186:189], v[104:107]
	v_mfma_f32_16x16x32_bf16 v[84:87], v[148:151], v[194:197], v[84:87]
	v_mfma_f32_16x16x32_bf16 v[80:83], v[170:173], v[194:197], v[80:83]
	v_mfma_f32_16x16x32_bf16 v[68:71], v[148:151], v[202:205], v[68:71]
	v_mfma_f32_16x16x32_bf16 v[64:67], v[170:173], v[202:205], v[64:67]
	s_barrier
	s_setprio 0
	s_add_i32 s20, s55, s56
	v_lshl_add_u64 v[166:167], v[166:167], 0, s[36:37]
	s_mov_b32 m0, s20
	ds_read_b128 v[174:177], v211 offset:49152
	ds_read_b128 v[178:181], v211 offset:50176
	ds_read_b128 v[182:185], v211 offset:51200
	ds_read_b128 v[186:189], v211 offset:52224
	ds_read_b128 v[190:193], v211 offset:53248
	ds_read_b128 v[194:197], v211 offset:54272
	ds_read_b128 v[198:201], v211 offset:55296
	ds_read_b128 v[202:205], v211 offset:56320
	global_load_lds_dwordx4 v[166:167], off
	v_lshl_add_u64 v[166:167], v[212:213], 0, s[36:37]
	s_add_i32 m0, s20, 0x2000
	s_add_i32 s20, s72, s56
	global_load_lds_dwordx4 v[166:167], off
	v_lshl_add_u64 v[166:167], v[214:215], 0, s[36:37]
	s_mov_b32 m0, s20
	s_nop 0
	global_load_lds_dwordx4 v[166:167], off
	v_lshl_add_u64 v[166:167], v[216:217], 0, s[36:37]
	s_add_i32 m0, s20, 0x2000
	s_nop 0
	global_load_lds_dwordx4 v[166:167], off
	v_lshl_add_u64 v[166:167], v[218:219], 0, s[36:37]
	s_mov_b32 m0, s66
	s_nop 0
	global_load_lds_dwordx4 v[166:167], off
	v_lshl_add_u64 v[166:167], v[220:221], 0, s[36:37]
	s_mov_b32 m0, s67
	s_nop 0
	global_load_lds_dwordx4 v[166:167], off
	s_waitcnt vmcnt(8)
	s_waitcnt lgkmcnt(0)
	s_setprio 1
	s_barrier
	v_mfma_f32_16x16x32_bf16 v[60:63], v[88:91], v[174:177], v[60:63]
	v_mfma_f32_16x16x32_bf16 v[56:59], v[112:115], v[174:177], v[56:59]
	v_mfma_f32_16x16x32_bf16 v[44:47], v[88:91], v[182:185], v[44:47]
	v_mfma_f32_16x16x32_bf16 v[40:43], v[112:115], v[182:185], v[40:43]
	v_mfma_f32_16x16x32_bf16 v[28:31], v[88:91], v[190:193], v[28:31]
	v_mfma_f32_16x16x32_bf16 v[24:27], v[112:115], v[190:193], v[24:27]
	v_mfma_f32_16x16x32_bf16 v[12:15], v[88:91], v[198:201], v[12:15]
	v_mfma_f32_16x16x32_bf16 v[8:11], v[112:115], v[198:201], v[8:11]
	v_mfma_f32_16x16x32_bf16 v[60:63], v[100:103], v[178:181], v[60:63]
	v_mfma_f32_16x16x32_bf16 v[56:59], v[124:127], v[178:181], v[56:59]
	v_mfma_f32_16x16x32_bf16 v[44:47], v[100:103], v[186:189], v[44:47]
	v_mfma_f32_16x16x32_bf16 v[40:43], v[124:127], v[186:189], v[40:43]
	v_mfma_f32_16x16x32_bf16 v[28:31], v[100:103], v[194:197], v[28:31]
	v_mfma_f32_16x16x32_bf16 v[24:27], v[124:127], v[194:197], v[24:27]
	v_mfma_f32_16x16x32_bf16 v[12:15], v[100:103], v[202:205], v[12:15]
	v_mfma_f32_16x16x32_bf16 v[8:11], v[124:127], v[202:205], v[8:11]
	v_mfma_f32_16x16x32_bf16 v[52:55], v[136:139], v[174:177], v[52:55]
	v_mfma_f32_16x16x32_bf16 v[48:51], v[152:155], v[174:177], v[48:51]
	v_mfma_f32_16x16x32_bf16 v[36:39], v[136:139], v[182:185], v[36:39]
	v_mfma_f32_16x16x32_bf16 v[32:35], v[152:155], v[182:185], v[32:35]
	v_mfma_f32_16x16x32_bf16 v[20:23], v[136:139], v[190:193], v[20:23]
	v_mfma_f32_16x16x32_bf16 v[16:19], v[152:155], v[190:193], v[16:19]
	v_mfma_f32_16x16x32_bf16 v[4:7], v[136:139], v[198:201], v[4:7]
	v_mfma_f32_16x16x32_bf16 v[0:3], v[152:155], v[198:201], v[0:3]
	v_mfma_f32_16x16x32_bf16 v[52:55], v[148:151], v[178:181], v[52:55]
	v_mfma_f32_16x16x32_bf16 v[48:51], v[170:173], v[178:181], v[48:51]
	v_mfma_f32_16x16x32_bf16 v[36:39], v[148:151], v[186:189], v[36:39]
	v_mfma_f32_16x16x32_bf16 v[32:35], v[170:173], v[186:189], v[32:35]
	v_mfma_f32_16x16x32_bf16 v[20:23], v[148:151], v[194:197], v[20:23]
	v_mfma_f32_16x16x32_bf16 v[16:19], v[170:173], v[194:197], v[16:19]
	v_mfma_f32_16x16x32_bf16 v[4:7], v[148:151], v[202:205], v[4:7]
	v_mfma_f32_16x16x32_bf16 v[0:3], v[170:173], v[202:205], v[0:3]
	s_barrier
	s_setprio 0
	s_add_u32 s44, s44, 0x100
	s_addc_u32 s45, s45, 0
	s_add_u32 s42, s42, 0x100
	s_addc_u32 s43, s43, 0
	s_cmp_ge_u32 s54, s3
	s_mov_b32 s20, s54
	s_cbranch_scc0 .LBB0_575
	s_and_b64 vcc, exec, s[16:17]
	s_cbranch_vccz .LBB0_578
	s_barrier

.LBB0_692:
	s_add_u32 s20, s40, 0xfffc0080
	s_addc_u32 s21, s41, -1
	s_add_i32 s71, 0, 0x10000
	s_cmp_eq_u32 s70, 12
	s_cselect_b32 s51, s43, s21
	s_cselect_b32 s50, s66, s20
	s_cselect_b32 s21, s19, s69
	s_cselect_b32 s20, s67, s68
	s_add_i32 s74, 0, 0x14000
	v_add_u32_e32 v150, s71, v156
	v_add_u32_e32 v188, s74, v156
	ds_read_b128 v[138:141], v150
	ds_read_b128 v[142:145], v150 offset:1024
	ds_read_b128 v[146:149], v150 offset:2048
	ds_read_b128 v[150:153], v150 offset:3072
	ds_read_b128 v[176:179], v188
	ds_read_b128 v[180:183], v188 offset:1024
	ds_read_b128 v[184:187], v188 offset:2048
	ds_read_b128 v[188:191], v188 offset:3072
	v_lshl_add_u64 v[224:225], s[40:41], 0, v[136:137]
	s_add_i32 m0, s57, 0xc000
	ds_read_b128 v[192:195], v175
	ds_read_b128 v[196:199], v175 offset:1024
	ds_read_b128 v[200:203], v175 offset:2048
	ds_read_b128 v[204:207], v175 offset:3072
	ds_read_b128 v[208:211], v175 offset:4096
	ds_read_b128 v[212:215], v175 offset:5120
	ds_read_b128 v[216:219], v175 offset:6144
	ds_read_b128 v[220:223], v175 offset:7168
	global_load_lds_dwordx4 v[224:225], off
	v_lshl_add_u64 v[224:225], s[40:41], 0, v[134:135]
	s_add_i32 m0, s57, 0xe000
	s_nop 0
	global_load_lds_dwordx4 v[224:225], off
	s_waitcnt vmcnt(8)
	s_waitcnt lgkmcnt(0)
	s_setprio 1
	s_barrier
	v_mfma_f32_16x16x32_bf16 v[124:127], v[138:141], v[192:195], v[124:127]
	v_mfma_f32_16x16x32_bf16 v[112:115], v[146:149], v[192:195], v[112:115]
	v_mfma_f32_16x16x32_bf16 v[108:111], v[138:141], v[200:203], v[108:111]
	v_mfma_f32_16x16x32_bf16 v[96:99], v[146:149], v[200:203], v[96:99]
	v_mfma_f32_16x16x32_bf16 v[92:95], v[138:141], v[208:211], v[92:95]
	v_mfma_f32_16x16x32_bf16 v[80:83], v[146:149], v[208:211], v[80:83]
	v_mfma_f32_16x16x32_bf16 v[76:79], v[138:141], v[216:219], v[76:79]
	v_mfma_f32_16x16x32_bf16 v[64:67], v[146:149], v[216:219], v[64:67]
	v_mfma_f32_16x16x32_bf16 v[124:127], v[142:145], v[196:199], v[124:127]
	v_mfma_f32_16x16x32_bf16 v[112:115], v[150:153], v[196:199], v[112:115]
	v_mfma_f32_16x16x32_bf16 v[108:111], v[142:145], v[204:207], v[108:111]
	v_mfma_f32_16x16x32_bf16 v[96:99], v[150:153], v[204:207], v[96:99]
	v_mfma_f32_16x16x32_bf16 v[92:95], v[142:145], v[212:215], v[92:95]
	v_mfma_f32_16x16x32_bf16 v[80:83], v[150:153], v[212:215], v[80:83]
	v_mfma_f32_16x16x32_bf16 v[76:79], v[142:145], v[220:223], v[76:79]
	v_mfma_f32_16x16x32_bf16 v[64:67], v[150:153], v[220:223], v[64:67]
	v_mfma_f32_16x16x32_bf16 v[120:123], v[176:179], v[192:195], v[120:123]
	v_mfma_f32_16x16x32_bf16 v[116:119], v[184:187], v[192:195], v[116:119]
	v_mfma_f32_16x16x32_bf16 v[104:107], v[176:179], v[200:203], v[104:107]
	v_mfma_f32_16x16x32_bf16 v[100:103], v[184:187], v[200:203], v[100:103]
	v_mfma_f32_16x16x32_bf16 v[88:91], v[176:179], v[208:211], v[88:91]
	v_mfma_f32_16x16x32_bf16 v[84:87], v[184:187], v[208:211], v[84:87]
	v_mfma_f32_16x16x32_bf16 v[72:75], v[176:179], v[216:219], v[72:75]
	v_mfma_f32_16x16x32_bf16 v[68:71], v[184:187], v[216:219], v[68:71]
	v_mfma_f32_16x16x32_bf16 v[120:123], v[180:183], v[196:199], v[120:123]
	v_mfma_f32_16x16x32_bf16 v[116:119], v[188:191], v[196:199], v[116:119]
	v_mfma_f32_16x16x32_bf16 v[104:107], v[180:183], v[204:207], v[104:107]
	v_mfma_f32_16x16x32_bf16 v[100:103], v[188:191], v[204:207], v[100:103]
	v_mfma_f32_16x16x32_bf16 v[88:91], v[180:183], v[212:215], v[88:91]
	v_mfma_f32_16x16x32_bf16 v[84:87], v[188:191], v[212:215], v[84:87]
	v_mfma_f32_16x16x32_bf16 v[72:75], v[180:183], v[220:223], v[72:75]
	v_mfma_f32_16x16x32_bf16 v[68:71], v[188:191], v[220:223], v[68:71]
	s_barrier
	s_setprio 0
	s_add_i32 s71, s71, s54
	v_lshl_add_u64 v[224:225], s[20:21], 0, v[168:169]
	s_mov_b32 m0, s71
	ds_read_b128 v[192:195], v175 offset:16384
	ds_read_b128 v[196:199], v175 offset:17408
	ds_read_b128 v[200:203], v175 offset:18432
	ds_read_b128 v[204:207], v175 offset:19456
	ds_read_b128 v[208:211], v175 offset:20480
	ds_read_b128 v[212:215], v175 offset:21504
	ds_read_b128 v[216:219], v175 offset:22528
	ds_read_b128 v[220:223], v175 offset:23552
	global_load_lds_dwordx4 v[224:225], off
	s_add_i32 m0, s71, 0x2000
	s_add_u32 s72, s20, 0x40000
	v_lshl_add_u64 v[226:227], s[20:21], 0, v[128:129]
	s_addc_u32 s73, s21, 0
	s_add_i32 s71, s74, s54
	global_load_lds_dwordx4 v[226:227], off
	v_lshl_add_u64 v[228:229], s[72:73], 0, v[168:169]
	s_mov_b32 m0, s71
	v_lshl_add_u64 v[230:231], s[50:51], 0, v[130:131]
	global_load_lds_dwordx4 v[228:229], off
	v_lshl_add_u64 v[228:229], s[72:73], 0, v[128:129]
	s_add_i32 m0, s71, 0x2000
	s_nop 0
	global_load_lds_dwordx4 v[228:229], off
	v_lshl_add_u64 v[228:229], s[50:51], 0, v[132:133]
	s_mov_b32 m0, s57
	s_nop 0
	global_load_lds_dwordx4 v[228:229], off
	s_mov_b32 m0, s58
	s_nop 0
	global_load_lds_dwordx4 v[230:231], off
	s_waitcnt vmcnt(8)
	s_waitcnt lgkmcnt(0)
	s_setprio 1
	s_barrier
	v_mfma_f32_16x16x32_bf16 v[60:63], v[138:141], v[192:195], v[60:63]
	v_mfma_f32_16x16x32_bf16 v[48:51], v[146:149], v[192:195], v[48:51]
	v_mfma_f32_16x16x32_bf16 v[44:47], v[138:141], v[200:203], v[44:47]
	v_mfma_f32_16x16x32_bf16 v[32:35], v[146:149], v[200:203], v[32:35]
	v_mfma_f32_16x16x32_bf16 v[28:31], v[138:141], v[208:211], v[28:31]
	v_mfma_f32_16x16x32_bf16 v[16:19], v[146:149], v[208:211], v[16:19]
	v_mfma_f32_16x16x32_bf16 v[12:15], v[138:141], v[216:219], v[12:15]
	v_mfma_f32_16x16x32_bf16 v[4:7], v[146:149], v[216:219], v[4:7]
	v_mfma_f32_16x16x32_bf16 v[60:63], v[142:145], v[196:199], v[60:63]
	v_mfma_f32_16x16x32_bf16 v[48:51], v[150:153], v[196:199], v[48:51]
	v_mfma_f32_16x16x32_bf16 v[44:47], v[142:145], v[204:207], v[44:47]
	v_mfma_f32_16x16x32_bf16 v[32:35], v[150:153], v[204:207], v[32:35]
	v_mfma_f32_16x16x32_bf16 v[28:31], v[142:145], v[212:215], v[28:31]
	v_mfma_f32_16x16x32_bf16 v[16:19], v[150:153], v[212:215], v[16:19]
	v_mfma_f32_16x16x32_bf16 v[12:15], v[142:145], v[220:223], v[12:15]
	v_mfma_f32_16x16x32_bf16 v[4:7], v[150:153], v[220:223], v[4:7]
	v_mfma_f32_16x16x32_bf16 v[56:59], v[176:179], v[192:195], v[56:59]
	v_mfma_f32_16x16x32_bf16 v[52:55], v[184:187], v[192:195], v[52:55]
	v_mfma_f32_16x16x32_bf16 v[40:43], v[176:179], v[200:203], v[40:43]
	v_mfma_f32_16x16x32_bf16 v[36:39], v[184:187], v[200:203], v[36:39]
	v_mfma_f32_16x16x32_bf16 v[24:27], v[176:179], v[208:211], v[24:27]
	v_mfma_f32_16x16x32_bf16 v[20:23], v[184:187], v[208:211], v[20:23]
	v_mfma_f32_16x16x32_bf16 v[8:11], v[176:179], v[216:219], v[8:11]
	v_mfma_f32_16x16x32_bf16 v[0:3], v[184:187], v[216:219], v[0:3]
	v_mfma_f32_16x16x32_bf16 v[56:59], v[180:183], v[196:199], v[56:59]
	v_mfma_f32_16x16x32_bf16 v[52:55], v[188:191], v[196:199], v[52:55]
	v_mfma_f32_16x16x32_bf16 v[40:43], v[180:183], v[204:207], v[40:43]
	v_mfma_f32_16x16x32_bf16 v[36:39], v[188:191], v[204:207], v[36:39]
	v_mfma_f32_16x16x32_bf16 v[24:27], v[180:183], v[212:215], v[24:27]
	v_mfma_f32_16x16x32_bf16 v[20:23], v[188:191], v[212:215], v[20:23]
	v_mfma_f32_16x16x32_bf16 v[8:11], v[180:183], v[220:223], v[8:11]
	v_mfma_f32_16x16x32_bf16 v[0:3], v[188:191], v[220:223], v[0:3]
	s_barrier
	s_setprio 0
	s_add_i32 s71, 0, 0x18000
	s_add_i32 s72, 0, 0x1c000
	v_add_u32_e32 v150, s71, v156
	v_add_u32_e32 v188, s72, v156
	ds_read_b128 v[138:141], v150
	ds_read_b128 v[142:145], v150 offset:1024
	ds_read_b128 v[146:149], v150 offset:2048
	ds_read_b128 v[150:153], v150 offset:3072
	ds_read_b128 v[176:179], v188
	ds_read_b128 v[180:183], v188 offset:1024
	ds_read_b128 v[184:187], v188 offset:2048
	ds_read_b128 v[188:191], v188 offset:3072
	s_add_u32 s50, s50, 0x40000
	s_addc_u32 s51, s51, 0
	s_mov_b32 m0, s59
	v_lshl_add_u64 v[232:233], s[50:51], 0, v[132:133]
	ds_read_b128 v[192:195], v175 offset:32768
	ds_read_b128 v[196:199], v175 offset:33792
	ds_read_b128 v[200:203], v175 offset:34816
	ds_read_b128 v[204:207], v175 offset:35840
	ds_read_b128 v[208:211], v175 offset:36864
	ds_read_b128 v[212:215], v175 offset:37888
	ds_read_b128 v[216:219], v175 offset:38912
	ds_read_b128 v[220:223], v175 offset:39936
	global_load_lds_dwordx4 v[232:233], off
	v_lshl_add_u64 v[232:233], s[50:51], 0, v[130:131]
	s_mov_b32 m0, s60
	s_nop 0
	global_load_lds_dwordx4 v[232:233], off
	s_waitcnt vmcnt(8)
	s_waitcnt lgkmcnt(0)
	s_setprio 1
	s_barrier
	v_mfma_f32_16x16x32_bf16 v[124:127], v[138:141], v[192:195], v[124:127]
	v_mfma_f32_16x16x32_bf16 v[112:115], v[146:149], v[192:195], v[112:115]
	v_mfma_f32_16x16x32_bf16 v[108:111], v[138:141], v[200:203], v[108:111]
	v_mfma_f32_16x16x32_bf16 v[96:99], v[146:149], v[200:203], v[96:99]
	v_mfma_f32_16x16x32_bf16 v[92:95], v[138:141], v[208:211], v[92:95]
	v_mfma_f32_16x16x32_bf16 v[80:83], v[146:149], v[208:211], v[80:83]
	v_mfma_f32_16x16x32_bf16 v[76:79], v[138:141], v[216:219], v[76:79]
	v_mfma_f32_16x16x32_bf16 v[64:67], v[146:149], v[216:219], v[64:67]
	v_mfma_f32_16x16x32_bf16 v[124:127], v[142:145], v[196:199], v[124:127]
	v_mfma_f32_16x16x32_bf16 v[112:115], v[150:153], v[196:199], v[112:115]
	v_mfma_f32_16x16x32_bf16 v[108:111], v[142:145], v[204:207], v[108:111]
	v_mfma_f32_16x16x32_bf16 v[96:99], v[150:153], v[204:207], v[96:99]
	v_mfma_f32_16x16x32_bf16 v[92:95], v[142:145], v[212:215], v[92:95]
	v_mfma_f32_16x16x32_bf16 v[80:83], v[150:153], v[212:215], v[80:83]
	v_mfma_f32_16x16x32_bf16 v[76:79], v[142:145], v[220:223], v[76:79]
	v_mfma_f32_16x16x32_bf16 v[64:67], v[150:153], v[220:223], v[64:67]
	v_mfma_f32_16x16x32_bf16 v[120:123], v[176:179], v[192:195], v[120:123]
	v_mfma_f32_16x16x32_bf16 v[116:119], v[184:187], v[192:195], v[116:119]
	v_mfma_f32_16x16x32_bf16 v[104:107], v[176:179], v[200:203], v[104:107]
	v_mfma_f32_16x16x32_bf16 v[100:103], v[184:187], v[200:203], v[100:103]
	v_mfma_f32_16x16x32_bf16 v[88:91], v[176:179], v[208:211], v[88:91]
	v_mfma_f32_16x16x32_bf16 v[84:87], v[184:187], v[208:211], v[84:87]
	v_mfma_f32_16x16x32_bf16 v[72:75], v[176:179], v[216:219], v[72:75]
	v_mfma_f32_16x16x32_bf16 v[68:71], v[184:187], v[216:219], v[68:71]
	v_mfma_f32_16x16x32_bf16 v[120:123], v[180:183], v[196:199], v[120:123]
	v_mfma_f32_16x16x32_bf16 v[116:119], v[188:191], v[196:199], v[116:119]
	v_mfma_f32_16x16x32_bf16 v[104:107], v[180:183], v[204:207], v[104:107]
	v_mfma_f32_16x16x32_bf16 v[100:103], v[188:191], v[204:207], v[100:103]
	v_mfma_f32_16x16x32_bf16 v[88:91], v[180:183], v[212:215], v[88:91]
	v_mfma_f32_16x16x32_bf16 v[84:87], v[188:191], v[212:215], v[84:87]
	v_mfma_f32_16x16x32_bf16 v[72:75], v[180:183], v[220:223], v[72:75]
	v_mfma_f32_16x16x32_bf16 v[68:71], v[188:191], v[220:223], v[68:71]
	s_barrier
	s_setprio 0
	s_add_i32 s50, s71, s54
	v_lshl_add_u64 v[224:225], v[224:225], 0, s[36:37]
	s_mov_b32 m0, s50
	ds_read_b128 v[192:195], v175 offset:49152
	ds_read_b128 v[196:199], v175 offset:50176
	ds_read_b128 v[200:203], v175 offset:51200
	ds_read_b128 v[204:207], v175 offset:52224
	ds_read_b128 v[208:211], v175 offset:53248
	ds_read_b128 v[212:215], v175 offset:54272
	ds_read_b128 v[216:219], v175 offset:55296
	ds_read_b128 v[220:223], v175 offset:56320
	global_load_lds_dwordx4 v[224:225], off
	s_add_i32 m0, s50, 0x2000
	s_add_u32 s20, s20, 0x40080
	v_lshl_add_u64 v[224:225], v[226:227], 0, s[36:37]
	s_addc_u32 s21, s21, 0
	s_add_i32 s50, s72, s54
	global_load_lds_dwordx4 v[224:225], off
	v_lshl_add_u64 v[224:225], s[20:21], 0, v[168:169]
	s_mov_b32 m0, s50
	s_nop 0
	global_load_lds_dwordx4 v[224:225], off
	v_lshl_add_u64 v[224:225], s[20:21], 0, v[128:129]
	s_add_i32 m0, s50, 0x2000
	s_nop 0
	global_load_lds_dwordx4 v[224:225], off
	v_lshl_add_u64 v[224:225], v[228:229], 0, s[36:37]
	s_mov_b32 m0, s61
	s_nop 0
	global_load_lds_dwordx4 v[224:225], off
	v_lshl_add_u64 v[224:225], v[230:231], 0, s[36:37]
	s_mov_b32 m0, s62
	s_nop 0
	global_load_lds_dwordx4 v[224:225], off
	s_waitcnt vmcnt(8)
	s_waitcnt lgkmcnt(0)
	s_setprio 1
	s_barrier
	v_mfma_f32_16x16x32_bf16 v[60:63], v[138:141], v[192:195], v[60:63]
	v_mfma_f32_16x16x32_bf16 v[48:51], v[146:149], v[192:195], v[48:51]
	v_mfma_f32_16x16x32_bf16 v[44:47], v[138:141], v[200:203], v[44:47]
	v_mfma_f32_16x16x32_bf16 v[32:35], v[146:149], v[200:203], v[32:35]
	v_mfma_f32_16x16x32_bf16 v[28:31], v[138:141], v[208:211], v[28:31]
	v_mfma_f32_16x16x32_bf16 v[16:19], v[146:149], v[208:211], v[16:19]
	v_mfma_f32_16x16x32_bf16 v[12:15], v[138:141], v[216:219], v[12:15]
	v_mfma_f32_16x16x32_bf16 v[4:7], v[146:149], v[216:219], v[4:7]
	v_mfma_f32_16x16x32_bf16 v[60:63], v[142:145], v[196:199], v[60:63]
	v_mfma_f32_16x16x32_bf16 v[48:51], v[150:153], v[196:199], v[48:51]
	v_mfma_f32_16x16x32_bf16 v[44:47], v[142:145], v[204:207], v[44:47]
	v_mfma_f32_16x16x32_bf16 v[32:35], v[150:153], v[204:207], v[32:35]
	v_mfma_f32_16x16x32_bf16 v[28:31], v[142:145], v[212:215], v[28:31]
	v_mfma_f32_16x16x32_bf16 v[16:19], v[150:153], v[212:215], v[16:19]
	v_mfma_f32_16x16x32_bf16 v[12:15], v[142:145], v[220:223], v[12:15]
	v_mfma_f32_16x16x32_bf16 v[4:7], v[150:153], v[220:223], v[4:7]
	v_mfma_f32_16x16x32_bf16 v[56:59], v[176:179], v[192:195], v[56:59]
	v_mfma_f32_16x16x32_bf16 v[52:55], v[184:187], v[192:195], v[52:55]
	v_mfma_f32_16x16x32_bf16 v[40:43], v[176:179], v[200:203], v[40:43]
	v_mfma_f32_16x16x32_bf16 v[36:39], v[184:187], v[200:203], v[36:39]
	v_mfma_f32_16x16x32_bf16 v[24:27], v[176:179], v[208:211], v[24:27]
	v_mfma_f32_16x16x32_bf16 v[20:23], v[184:187], v[208:211], v[20:23]
	v_mfma_f32_16x16x32_bf16 v[8:11], v[176:179], v[216:219], v[8:11]
	v_mfma_f32_16x16x32_bf16 v[0:3], v[184:187], v[216:219], v[0:3]
	v_mfma_f32_16x16x32_bf16 v[56:59], v[180:183], v[196:199], v[56:59]
	v_mfma_f32_16x16x32_bf16 v[52:55], v[188:191], v[196:199], v[52:55]
	v_mfma_f32_16x16x32_bf16 v[40:43], v[180:183], v[204:207], v[40:43]
	v_mfma_f32_16x16x32_bf16 v[36:39], v[188:191], v[204:207], v[36:39]
	v_mfma_f32_16x16x32_bf16 v[24:27], v[180:183], v[212:215], v[24:27]
	v_mfma_f32_16x16x32_bf16 v[20:23], v[188:191], v[212:215], v[20:23]
	v_mfma_f32_16x16x32_bf16 v[8:11], v[180:183], v[220:223], v[8:11]
	v_mfma_f32_16x16x32_bf16 v[0:3], v[188:191], v[220:223], v[0:3]
	s_barrier
	s_setprio 0
	s_add_i32 s70, s70, 2
	s_add_u32 s68, s68, 0x100
	s_addc_u32 s69, s69, 0
	s_add_u32 s40, s40, 0x100
	s_addc_u32 s41, s41, 0
	s_cmp_gt_u32 s70, 13
	s_cbranch_scc0 .LBB0_692
	s_and_b64 vcc, exec, s[16:17]
	s_cbranch_vccz .LBB0_695
	s_barrier
